# P5 prompt tiles: single accumulator chain sgb*(accA*sga/sgb + accB) in f32 instead of the bf16 MG round trip between the two GEMMs (one epilogue, second GEMM continues on the scaled accumulators)
# speedup vs baseline: 1.0186x; 1.0186x over previous
; __device__ __forceinline__ unsigned pk2(float lo, float hi) { const f32x2_t_ v = {lo, hi}; return __builtin_bit_cast(unsigned, __builtin_convertvector(v, bf16x2_t_)); }
;     __device__ __forceinline__ Pre pre4(int row, int col) const { const float* sb = (row < TP) ? srcP : srcS - (size_t)TP * DM; Pre p; p.s = NTL((const f32x4*)(sb + (size_t)row * DM + col)); return p; }
;     __device__ __forceinline__ float store4p(int row, int col, f32x4 a, const Pre& p) const {
;         const size_t o = (size_t)row * DM + col;
;         float r0 = bflo(p.g.x) * a[0], r1 = bfhi(p.g.x) * a[1], r2 = bflo(p.g.y) * a[2], r3 = bfhi(p.g.y) * a[3];
;         if (MODE == 1) { r0 += bflo(p.m.x); r1 += bfhi(p.m.x); r2 += bflo(p.m.y); r3 += bfhi(p.m.y); }
;         v2u w; w.x = pk2(r0, r1); w.y = pk2(r2, r3); *(v2u*)(MG + o) = w; return 0.f;
;     }
;     __device__ __forceinline__ float store4(int row, int col, f32x4 a) const {
;         const size_t o = (size_t)row * DM + col; const v2u g = NTL((const v2u*)(SG + o));
;         float r0 = bflo(g.x) * a[0], r1 = bfhi(g.x) * a[1], r2 = bflo(g.y) * a[2], r3 = bfhi(g.y) * a[3];
;         if (MODE == 1) { const v2u p = NTL((const v2u*)(MG + o)); r0 += bflo(p.x); r1 += bfhi(p.x); r2 += bflo(p.y); r3 += bfhi(p.y); }
;         v2u w; w.x = pk2(r0, r1); w.y = pk2(r2, r3); *(v2u*)(MG + o) = w; return 0.f;
;     }
;     __device__ __forceinline__ void operator()(const f32x4 (&acc)[2][2][4][2], const Unit& u, int wr, int wc, int fr, int fq) const {
;         const int row0 = u.pm * BM + wr * 64 + fr, col0 = u.pn * BM + wc * 32 + 4 * fq;
; #pragma unroll
;         for (int am = 0; am < 4; ++am) {
;             const int ai = am >> 1, mb = (am & 1) * 2;
;             Pre pv[2][2][2];
; #pragma unroll
;             for (int mm = 0; mm < 2; ++mm)
; #pragma unroll
;                 for (int bj = 0; bj < 2; ++bj)
; #pragma unroll
;                     for (int n = 0; n < 2; ++n) pv[mm][bj][n] = pre4(row0 + ai * HALF + (mb + mm) * 16, col0 + bj * HALF + n * 16);
; #pragma unroll
;             for (int mm = 0; mm < 2; ++mm)
; #pragma unroll
;                 for (int bj = 0; bj < 2; ++bj)
; #pragma unroll
;                     for (int n = 0; n < 2; ++n) (void)store4p(row0 + ai * HALF + (mb + mm) * 16, col0 + bj * HALF + n * 16, acc[ai][bj][mb + mm][n], pv[mm][bj][n]);
.LBB0_1580:
	s_lshl_b32 s100, s58, 19
	s_lshl_b32 s101, s77, 9
	s_add_i32 s100, s100, s101
	s_add_u32 s98, s22, 0x6480000
	s_addc_u32 s99, s23, 0
	s_add_u32 s98, s98, s100
	s_addc_u32 s99, s99, 0
	s_add_u32 s100, s28, s100
	s_addc_u32 s101, s29, 0
	v_lshlrev_b32_e32 v142, 11, v157
	v_lshl_add_u32 v142, v159, 1, v142
	v_mov_b32_e32 v143, v142
	global_load_dwordx2 v[164:165], v143, s[100:101]
	global_load_dwordx2 v[166:167], v143, s[100:101] offset:32
	global_load_dwordx2 v[168:169], v143, s[100:101] offset:256
	global_load_dwordx2 v[170:171], v143, s[100:101] offset:288
	global_load_dwordx2 v[172:173], v143, s[98:99]
	global_load_dwordx2 v[174:175], v143, s[98:99] offset:32
	global_load_dwordx2 v[176:177], v143, s[98:99] offset:256
	global_load_dwordx2 v[178:179], v143, s[98:99] offset:288
	v_add_u32_e32 v143, 0x8000, v142
	global_load_dwordx2 v[180:181], v143, s[100:101]
	global_load_dwordx2 v[182:183], v143, s[100:101] offset:32
	global_load_dwordx2 v[184:185], v143, s[100:101] offset:256
	global_load_dwordx2 v[186:187], v143, s[100:101] offset:288
	global_load_dwordx2 v[188:189], v143, s[98:99]
	global_load_dwordx2 v[190:191], v143, s[98:99] offset:32
	global_load_dwordx2 v[192:193], v143, s[98:99] offset:256
	global_load_dwordx2 v[194:195], v143, s[98:99] offset:288
	v_add_u32_e32 v143, 0x10000, v142
	global_load_dwordx2 v[196:197], v143, s[100:101]
	global_load_dwordx2 v[198:199], v143, s[100:101] offset:32
	global_load_dwordx2 v[200:201], v143, s[100:101] offset:256
	global_load_dwordx2 v[202:203], v143, s[100:101] offset:288
	global_load_dwordx2 v[204:205], v143, s[98:99]
	global_load_dwordx2 v[206:207], v143, s[98:99] offset:32
	global_load_dwordx2 v[208:209], v143, s[98:99] offset:256
	global_load_dwordx2 v[210:211], v143, s[98:99] offset:288
	s_waitcnt vmcnt(16)
	v_lshlrev_b32_e32 v148, 16, v172
	v_and_b32_e32 v149, 0xffff0000, v172
	v_lshlrev_b32_e32 v214, 16, v173
	v_and_b32_e32 v215, 0xffff0000, v173
	v_max_f32_e32 v148, 0x800000, v148
	v_max_f32_e32 v149, 0x800000, v149
	v_max_f32_e32 v214, 0x800000, v214
	v_max_f32_e32 v215, 0x800000, v215
	v_rcp_f32_e32 v148, v148
	v_rcp_f32_e32 v149, v149
	v_rcp_f32_e32 v214, v214
	v_rcp_f32_e32 v215, v215
	v_lshlrev_b32_e32 v144, 16, v164
	v_and_b32_e32 v145, 0xffff0000, v164
	v_lshlrev_b32_e32 v146, 16, v165
	v_and_b32_e32 v147, 0xffff0000, v165
	v_mul_f32_e32 v144, v144, v148
	v_mul_f32_e32 v145, v145, v149
	v_mul_f32_e32 v146, v146, v214
	v_mul_f32_e32 v147, v147, v215
	v_pk_mul_f32 v[126:127], v[126:127], v[144:145]
	v_pk_mul_f32 v[128:129], v[128:129], v[146:147]
	v_lshlrev_b32_e32 v148, 16, v174
	v_and_b32_e32 v149, 0xffff0000, v174
	v_lshlrev_b32_e32 v214, 16, v175
	v_and_b32_e32 v215, 0xffff0000, v175
	v_max_f32_e32 v148, 0x800000, v148
	v_max_f32_e32 v149, 0x800000, v149
	v_max_f32_e32 v214, 0x800000, v214
	v_max_f32_e32 v215, 0x800000, v215
	v_rcp_f32_e32 v148, v148
	v_rcp_f32_e32 v149, v149
	v_rcp_f32_e32 v214, v214
	v_rcp_f32_e32 v215, v215
	v_lshlrev_b32_e32 v144, 16, v166
	v_and_b32_e32 v145, 0xffff0000, v166
	v_lshlrev_b32_e32 v146, 16, v167
	v_and_b32_e32 v147, 0xffff0000, v167
	v_mul_f32_e32 v144, v144, v148
	v_mul_f32_e32 v145, v145, v149
	v_mul_f32_e32 v146, v146, v214
	v_mul_f32_e32 v147, v147, v215
	v_pk_mul_f32 v[122:123], v[122:123], v[144:145]
	v_pk_mul_f32 v[124:125], v[124:125], v[146:147]
	v_lshlrev_b32_e32 v148, 16, v176
	v_and_b32_e32 v149, 0xffff0000, v176
	v_lshlrev_b32_e32 v214, 16, v177
	v_and_b32_e32 v215, 0xffff0000, v177
	v_max_f32_e32 v148, 0x800000, v148
	v_max_f32_e32 v149, 0x800000, v149
	v_max_f32_e32 v214, 0x800000, v214
	v_max_f32_e32 v215, 0x800000, v215
	v_rcp_f32_e32 v148, v148
	v_rcp_f32_e32 v149, v149
	v_rcp_f32_e32 v214, v214
	v_rcp_f32_e32 v215, v215
	v_lshlrev_b32_e32 v144, 16, v168
	v_and_b32_e32 v145, 0xffff0000, v168
	v_lshlrev_b32_e32 v146, 16, v169
	v_and_b32_e32 v147, 0xffff0000, v169
	v_mul_f32_e32 v144, v144, v148
	v_mul_f32_e32 v145, v145, v149
	v_mul_f32_e32 v146, v146, v214
	v_mul_f32_e32 v147, v147, v215
	v_pk_mul_f32 v[114:115], v[114:115], v[144:145]
	v_pk_mul_f32 v[116:117], v[116:117], v[146:147]
	v_lshlrev_b32_e32 v148, 16, v178
	v_and_b32_e32 v149, 0xffff0000, v178
	v_lshlrev_b32_e32 v214, 16, v179
	v_and_b32_e32 v215, 0xffff0000, v179
	v_max_f32_e32 v148, 0x800000, v148
	v_max_f32_e32 v149, 0x800000, v149
	v_max_f32_e32 v214, 0x800000, v214
	v_max_f32_e32 v215, 0x800000, v215
	v_rcp_f32_e32 v148, v148
	v_rcp_f32_e32 v149, v149
	v_rcp_f32_e32 v214, v214
	v_rcp_f32_e32 v215, v215
	v_lshlrev_b32_e32 v144, 16, v170
	v_and_b32_e32 v145, 0xffff0000, v170
	v_lshlrev_b32_e32 v146, 16, v171
	v_and_b32_e32 v147, 0xffff0000, v171
	v_mul_f32_e32 v144, v144, v148
	v_mul_f32_e32 v145, v145, v149
	v_mul_f32_e32 v146, v146, v214
	v_mul_f32_e32 v147, v147, v215
	v_pk_mul_f32 v[110:111], v[110:111], v[144:145]
	v_pk_mul_f32 v[112:113], v[112:113], v[146:147]
	v_add_u32_e32 v143, 0x18000, v142
	global_load_dwordx2 v[164:165], v143, s[100:101]
	global_load_dwordx2 v[166:167], v143, s[100:101] offset:32
	global_load_dwordx2 v[168:169], v143, s[100:101] offset:256
	global_load_dwordx2 v[170:171], v143, s[100:101] offset:288
	global_load_dwordx2 v[172:173], v143, s[98:99]
	global_load_dwordx2 v[174:175], v143, s[98:99] offset:32
	global_load_dwordx2 v[176:177], v143, s[98:99] offset:256
	global_load_dwordx2 v[178:179], v143, s[98:99] offset:288
	s_waitcnt vmcnt(16)
; __device__ __forceinline__ unsigned pk2(float lo, float hi) { const f32x2_t_ v = {lo, hi}; return __builtin_bit_cast(unsigned, __builtin_convertvector(v, bf16x2_t_)); }
;     __device__ __forceinline__ Pre pre4(int row, int col) const { const float* sb = (row < TP) ? srcP : srcS - (size_t)TP * DM; Pre p; p.s = NTL((const f32x4*)(sb + (size_t)row * DM + col)); return p; }
;     __device__ __forceinline__ float store4p(int row, int col, f32x4 a, const Pre& p) const {
;         const size_t o = (size_t)row * DM + col;
;         float r0 = bflo(p.g.x) * a[0], r1 = bfhi(p.g.x) * a[1], r2 = bflo(p.g.y) * a[2], r3 = bfhi(p.g.y) * a[3];
;         if (MODE == 1) { r0 += bflo(p.m.x); r1 += bfhi(p.m.x); r2 += bflo(p.m.y); r3 += bfhi(p.m.y); }
;         v2u w; w.x = pk2(r0, r1); w.y = pk2(r2, r3); *(v2u*)(MG + o) = w; return 0.f;
;     }
;     __device__ __forceinline__ float store4(int row, int col, f32x4 a) const {
;         const size_t o = (size_t)row * DM + col; const v2u g = NTL((const v2u*)(SG + o));
;         float r0 = bflo(g.x) * a[0], r1 = bfhi(g.x) * a[1], r2 = bflo(g.y) * a[2], r3 = bfhi(g.y) * a[3];
;         if (MODE == 1) { const v2u p = NTL((const v2u*)(MG + o)); r0 += bflo(p.x); r1 += bfhi(p.x); r2 += bflo(p.y); r3 += bfhi(p.y); }
;         v2u w; w.x = pk2(r0, r1); w.y = pk2(r2, r3); *(v2u*)(MG + o) = w; return 0.f;
;     }
;     __device__ __forceinline__ void operator()(const f32x4 (&acc)[2][2][4][2], const Unit& u, int wr, int wc, int fr, int fq) const {
;         const int row0 = u.pm * BM + wr * 64 + fr, col0 = u.pn * BM + wc * 32 + 4 * fq;
; #pragma unroll
;         for (int am = 0; am < 4; ++am) {
;             const int ai = am >> 1, mb = (am & 1) * 2;
;             Pre pv[2][2][2];
; #pragma unroll
;             for (int mm = 0; mm < 2; ++mm)
; #pragma unroll
;                 for (int bj = 0; bj < 2; ++bj)
; #pragma unroll
;                     for (int n = 0; n < 2; ++n) pv[mm][bj][n] = pre4(row0 + ai * HALF + (mb + mm) * 16, col0 + bj * HALF + n * 16);
; #pragma unroll
;             for (int mm = 0; mm < 2; ++mm)
; #pragma unroll
;                 for (int bj = 0; bj < 2; ++bj)
; #pragma unroll
;                     for (int n = 0; n < 2; ++n) (void)store4p(row0 + ai * HALF + (mb + mm) * 16, col0 + bj * HALF + n * 16, acc[ai][bj][mb + mm][n], pv[mm][bj][n]);
	v_lshlrev_b32_e32 v148, 16, v188
	v_and_b32_e32 v149, 0xffff0000, v188
	v_lshlrev_b32_e32 v214, 16, v189
	v_and_b32_e32 v215, 0xffff0000, v189
	v_max_f32_e32 v148, 0x800000, v148
	v_max_f32_e32 v149, 0x800000, v149
	v_max_f32_e32 v214, 0x800000, v214
	v_max_f32_e32 v215, 0x800000, v215
	v_rcp_f32_e32 v148, v148
	v_rcp_f32_e32 v149, v149
	v_rcp_f32_e32 v214, v214
	v_rcp_f32_e32 v215, v215
	v_lshlrev_b32_e32 v144, 16, v180
	v_and_b32_e32 v145, 0xffff0000, v180
	v_lshlrev_b32_e32 v146, 16, v181
	v_and_b32_e32 v147, 0xffff0000, v181
	v_mul_f32_e32 v144, v144, v148
	v_mul_f32_e32 v145, v145, v149
	v_mul_f32_e32 v146, v146, v214
	v_mul_f32_e32 v147, v147, v215
	v_pk_mul_f32 v[118:119], v[118:119], v[144:145]
	v_pk_mul_f32 v[120:121], v[120:121], v[146:147]
	v_lshlrev_b32_e32 v148, 16, v190
	v_and_b32_e32 v149, 0xffff0000, v190
	v_lshlrev_b32_e32 v214, 16, v191
	v_and_b32_e32 v215, 0xffff0000, v191
	v_max_f32_e32 v148, 0x800000, v148
	v_max_f32_e32 v149, 0x800000, v149
	v_max_f32_e32 v214, 0x800000, v214
	v_max_f32_e32 v215, 0x800000, v215
	v_rcp_f32_e32 v148, v148
	v_rcp_f32_e32 v149, v149
	v_rcp_f32_e32 v214, v214
	v_rcp_f32_e32 v215, v215
	v_lshlrev_b32_e32 v144, 16, v182
	v_and_b32_e32 v145, 0xffff0000, v182
	v_lshlrev_b32_e32 v146, 16, v183
	v_and_b32_e32 v147, 0xffff0000, v183
	v_mul_f32_e32 v144, v144, v148
	v_mul_f32_e32 v145, v145, v149
	v_mul_f32_e32 v146, v146, v214
	v_mul_f32_e32 v147, v147, v215
	v_pk_mul_f32 v[106:107], v[106:107], v[144:145]
	v_pk_mul_f32 v[108:109], v[108:109], v[146:147]
	v_lshlrev_b32_e32 v148, 16, v192
	v_and_b32_e32 v149, 0xffff0000, v192
	v_lshlrev_b32_e32 v214, 16, v193
	v_and_b32_e32 v215, 0xffff0000, v193
	v_max_f32_e32 v148, 0x800000, v148
	v_max_f32_e32 v149, 0x800000, v149
	v_max_f32_e32 v214, 0x800000, v214
	v_max_f32_e32 v215, 0x800000, v215
	v_rcp_f32_e32 v148, v148
	v_rcp_f32_e32 v149, v149
	v_rcp_f32_e32 v214, v214
	v_rcp_f32_e32 v215, v215
	v_lshlrev_b32_e32 v144, 16, v184
	v_and_b32_e32 v145, 0xffff0000, v184
	v_lshlrev_b32_e32 v146, 16, v185
	v_and_b32_e32 v147, 0xffff0000, v185
	v_mul_f32_e32 v144, v144, v148
	v_mul_f32_e32 v145, v145, v149
	v_mul_f32_e32 v146, v146, v214
	v_mul_f32_e32 v147, v147, v215
	v_pk_mul_f32 v[102:103], v[102:103], v[144:145]
	v_pk_mul_f32 v[104:105], v[104:105], v[146:147]
	v_lshlrev_b32_e32 v148, 16, v194
	v_and_b32_e32 v149, 0xffff0000, v194
	v_lshlrev_b32_e32 v214, 16, v195
	v_and_b32_e32 v215, 0xffff0000, v195
	v_max_f32_e32 v148, 0x800000, v148
	v_max_f32_e32 v149, 0x800000, v149
	v_max_f32_e32 v214, 0x800000, v214
	v_max_f32_e32 v215, 0x800000, v215
	v_rcp_f32_e32 v148, v148
	v_rcp_f32_e32 v149, v149
	v_rcp_f32_e32 v214, v214
	v_rcp_f32_e32 v215, v215
	v_lshlrev_b32_e32 v144, 16, v186
	v_and_b32_e32 v145, 0xffff0000, v186
	v_lshlrev_b32_e32 v146, 16, v187
	v_and_b32_e32 v147, 0xffff0000, v187
	v_mul_f32_e32 v144, v144, v148
	v_mul_f32_e32 v145, v145, v149
	v_mul_f32_e32 v146, v146, v214
	v_mul_f32_e32 v147, v147, v215
	v_pk_mul_f32 v[94:95], v[94:95], v[144:145]
	v_pk_mul_f32 v[96:97], v[96:97], v[146:147]
	v_add_u32_e32 v143, 0x40000, v142
	global_load_dwordx2 v[180:181], v143, s[100:101]
	global_load_dwordx2 v[182:183], v143, s[100:101] offset:32
	global_load_dwordx2 v[184:185], v143, s[100:101] offset:256
	global_load_dwordx2 v[186:187], v143, s[100:101] offset:288
	global_load_dwordx2 v[188:189], v143, s[98:99]
	global_load_dwordx2 v[190:191], v143, s[98:99] offset:32
	global_load_dwordx2 v[192:193], v143, s[98:99] offset:256
	global_load_dwordx2 v[194:195], v143, s[98:99] offset:288
	s_waitcnt vmcnt(16)
	v_lshlrev_b32_e32 v148, 16, v204
	v_and_b32_e32 v149, 0xffff0000, v204
	v_lshlrev_b32_e32 v214, 16, v205
	v_and_b32_e32 v215, 0xffff0000, v205
	v_max_f32_e32 v148, 0x800000, v148
	v_max_f32_e32 v149, 0x800000, v149
	v_max_f32_e32 v214, 0x800000, v214
	v_max_f32_e32 v215, 0x800000, v215
	v_rcp_f32_e32 v148, v148
	v_rcp_f32_e32 v149, v149
	v_rcp_f32_e32 v214, v214
	v_rcp_f32_e32 v215, v215
	v_lshlrev_b32_e32 v144, 16, v196
	v_and_b32_e32 v145, 0xffff0000, v196
	v_lshlrev_b32_e32 v146, 16, v197
	v_and_b32_e32 v147, 0xffff0000, v197
	v_mul_f32_e32 v144, v144, v148
	v_mul_f32_e32 v145, v145, v149
	v_mul_f32_e32 v146, v146, v214
	v_mul_f32_e32 v147, v147, v215
	v_pk_mul_f32 v[98:99], v[98:99], v[144:145]
	v_pk_mul_f32 v[100:101], v[100:101], v[146:147]
	v_lshlrev_b32_e32 v148, 16, v206
	v_and_b32_e32 v149, 0xffff0000, v206
	v_lshlrev_b32_e32 v214, 16, v207
	v_and_b32_e32 v215, 0xffff0000, v207
	v_max_f32_e32 v148, 0x800000, v148
	v_max_f32_e32 v149, 0x800000, v149
	v_max_f32_e32 v214, 0x800000, v214
	v_max_f32_e32 v215, 0x800000, v215
	v_rcp_f32_e32 v148, v148
	v_rcp_f32_e32 v149, v149
	v_rcp_f32_e32 v214, v214
	v_rcp_f32_e32 v215, v215
	v_lshlrev_b32_e32 v144, 16, v198
	v_and_b32_e32 v145, 0xffff0000, v198
	v_lshlrev_b32_e32 v146, 16, v199
	v_and_b32_e32 v147, 0xffff0000, v199
	v_mul_f32_e32 v144, v144, v148
	v_mul_f32_e32 v145, v145, v149
	v_mul_f32_e32 v146, v146, v214
	v_mul_f32_e32 v147, v147, v215
	v_pk_mul_f32 v[90:91], v[90:91], v[144:145]
	v_pk_mul_f32 v[92:93], v[92:93], v[146:147]
	v_lshlrev_b32_e32 v148, 16, v208
	v_and_b32_e32 v149, 0xffff0000, v208
	v_lshlrev_b32_e32 v214, 16, v209
	v_and_b32_e32 v215, 0xffff0000, v209
	v_max_f32_e32 v148, 0x800000, v148
	v_max_f32_e32 v149, 0x800000, v149
	v_max_f32_e32 v214, 0x800000, v214
	v_max_f32_e32 v215, 0x800000, v215
	v_rcp_f32_e32 v148, v148
	v_rcp_f32_e32 v149, v149
	v_rcp_f32_e32 v214, v214
	v_rcp_f32_e32 v215, v215
	v_lshlrev_b32_e32 v144, 16, v200
	v_and_b32_e32 v145, 0xffff0000, v200
	v_lshlrev_b32_e32 v146, 16, v201
	v_and_b32_e32 v147, 0xffff0000, v201
	v_mul_f32_e32 v144, v144, v148
; __device__ __forceinline__ unsigned pk2(float lo, float hi) { const f32x2_t_ v = {lo, hi}; return __builtin_bit_cast(unsigned, __builtin_convertvector(v, bf16x2_t_)); }
;     __device__ __forceinline__ Pre pre4(int row, int col) const { const float* sb = (row < TP) ? srcP : srcS - (size_t)TP * DM; Pre p; p.s = NTL((const f32x4*)(sb + (size_t)row * DM + col)); return p; }
;     __device__ __forceinline__ float store4p(int row, int col, f32x4 a, const Pre& p) const {
;         const size_t o = (size_t)row * DM + col;
;         float r0 = bflo(p.g.x) * a[0], r1 = bfhi(p.g.x) * a[1], r2 = bflo(p.g.y) * a[2], r3 = bfhi(p.g.y) * a[3];
;         if (MODE == 1) { r0 += bflo(p.m.x); r1 += bfhi(p.m.x); r2 += bflo(p.m.y); r3 += bfhi(p.m.y); }
;         v2u w; w.x = pk2(r0, r1); w.y = pk2(r2, r3); *(v2u*)(MG + o) = w; return 0.f;
;     }
;     __device__ __forceinline__ float store4(int row, int col, f32x4 a) const {
;         const size_t o = (size_t)row * DM + col; const v2u g = NTL((const v2u*)(SG + o));
;         float r0 = bflo(g.x) * a[0], r1 = bfhi(g.x) * a[1], r2 = bflo(g.y) * a[2], r3 = bfhi(g.y) * a[3];
;         if (MODE == 1) { const v2u p = NTL((const v2u*)(MG + o)); r0 += bflo(p.x); r1 += bfhi(p.x); r2 += bflo(p.y); r3 += bfhi(p.y); }
;         v2u w; w.x = pk2(r0, r1); w.y = pk2(r2, r3); *(v2u*)(MG + o) = w; return 0.f;
;     }
;     __device__ __forceinline__ void operator()(const f32x4 (&acc)[2][2][4][2], const Unit& u, int wr, int wc, int fr, int fq) const {
;         const int row0 = u.pm * BM + wr * 64 + fr, col0 = u.pn * BM + wc * 32 + 4 * fq;
; #pragma unroll
;         for (int am = 0; am < 4; ++am) {
;             const int ai = am >> 1, mb = (am & 1) * 2;
;             Pre pv[2][2][2];
; #pragma unroll
;             for (int mm = 0; mm < 2; ++mm)
; #pragma unroll
;                 for (int bj = 0; bj < 2; ++bj)
; #pragma unroll
;                     for (int n = 0; n < 2; ++n) pv[mm][bj][n] = pre4(row0 + ai * HALF + (mb + mm) * 16, col0 + bj * HALF + n * 16);
; #pragma unroll
;             for (int mm = 0; mm < 2; ++mm)
; #pragma unroll
;                 for (int bj = 0; bj < 2; ++bj)
; #pragma unroll
;                     for (int n = 0; n < 2; ++n) (void)store4p(row0 + ai * HALF + (mb + mm) * 16, col0 + bj * HALF + n * 16, acc[ai][bj][mb + mm][n], pv[mm][bj][n]);
	v_mul_f32_e32 v145, v145, v149
	v_mul_f32_e32 v146, v146, v214
	v_mul_f32_e32 v147, v147, v215
	v_pk_mul_f32 v[82:83], v[82:83], v[144:145]
	v_pk_mul_f32 v[84:85], v[84:85], v[146:147]
	v_lshlrev_b32_e32 v148, 16, v210
	v_and_b32_e32 v149, 0xffff0000, v210
	v_lshlrev_b32_e32 v214, 16, v211
	v_and_b32_e32 v215, 0xffff0000, v211
	v_max_f32_e32 v148, 0x800000, v148
	v_max_f32_e32 v149, 0x800000, v149
	v_max_f32_e32 v214, 0x800000, v214
	v_max_f32_e32 v215, 0x800000, v215
	v_rcp_f32_e32 v148, v148
	v_rcp_f32_e32 v149, v149
	v_rcp_f32_e32 v214, v214
	v_rcp_f32_e32 v215, v215
	v_lshlrev_b32_e32 v144, 16, v202
	v_and_b32_e32 v145, 0xffff0000, v202
	v_lshlrev_b32_e32 v146, 16, v203
	v_and_b32_e32 v147, 0xffff0000, v203
	v_mul_f32_e32 v144, v144, v148
	v_mul_f32_e32 v145, v145, v149
	v_mul_f32_e32 v146, v146, v214
	v_mul_f32_e32 v147, v147, v215
	v_pk_mul_f32 v[78:79], v[78:79], v[144:145]
	v_pk_mul_f32 v[80:81], v[80:81], v[146:147]
	v_add_u32_e32 v143, 0x48000, v142
	global_load_dwordx2 v[196:197], v143, s[100:101]
	global_load_dwordx2 v[198:199], v143, s[100:101] offset:32
	global_load_dwordx2 v[200:201], v143, s[100:101] offset:256
	global_load_dwordx2 v[202:203], v143, s[100:101] offset:288
	global_load_dwordx2 v[204:205], v143, s[98:99]
	global_load_dwordx2 v[206:207], v143, s[98:99] offset:32
	global_load_dwordx2 v[208:209], v143, s[98:99] offset:256
	global_load_dwordx2 v[210:211], v143, s[98:99] offset:288
	s_waitcnt vmcnt(16)
	v_lshlrev_b32_e32 v148, 16, v172
	v_and_b32_e32 v149, 0xffff0000, v172
	v_lshlrev_b32_e32 v214, 16, v173
	v_and_b32_e32 v215, 0xffff0000, v173
	v_max_f32_e32 v148, 0x800000, v148
	v_max_f32_e32 v149, 0x800000, v149
	v_max_f32_e32 v214, 0x800000, v214
	v_max_f32_e32 v215, 0x800000, v215
	v_rcp_f32_e32 v148, v148
	v_rcp_f32_e32 v149, v149
	v_rcp_f32_e32 v214, v214
	v_rcp_f32_e32 v215, v215
	v_lshlrev_b32_e32 v144, 16, v164
	v_and_b32_e32 v145, 0xffff0000, v164
	v_lshlrev_b32_e32 v146, 16, v165
	v_and_b32_e32 v147, 0xffff0000, v165
	v_mul_f32_e32 v144, v144, v148
	v_mul_f32_e32 v145, v145, v149
	v_mul_f32_e32 v146, v146, v214
	v_mul_f32_e32 v147, v147, v215
	v_pk_mul_f32 v[86:87], v[86:87], v[144:145]
	v_pk_mul_f32 v[88:89], v[88:89], v[146:147]
	v_lshlrev_b32_e32 v148, 16, v174
	v_and_b32_e32 v149, 0xffff0000, v174
	v_lshlrev_b32_e32 v214, 16, v175
	v_and_b32_e32 v215, 0xffff0000, v175
	v_max_f32_e32 v148, 0x800000, v148
	v_max_f32_e32 v149, 0x800000, v149
	v_max_f32_e32 v214, 0x800000, v214
	v_max_f32_e32 v215, 0x800000, v215
	v_rcp_f32_e32 v148, v148
	v_rcp_f32_e32 v149, v149
	v_rcp_f32_e32 v214, v214
	v_rcp_f32_e32 v215, v215
	v_lshlrev_b32_e32 v144, 16, v166
	v_and_b32_e32 v145, 0xffff0000, v166
	v_lshlrev_b32_e32 v146, 16, v167
	v_and_b32_e32 v147, 0xffff0000, v167
	v_mul_f32_e32 v144, v144, v148
	v_mul_f32_e32 v145, v145, v149
	v_mul_f32_e32 v146, v146, v214
	v_mul_f32_e32 v147, v147, v215
	v_pk_mul_f32 v[74:75], v[74:75], v[144:145]
	v_pk_mul_f32 v[76:77], v[76:77], v[146:147]
	v_lshlrev_b32_e32 v148, 16, v176
	v_and_b32_e32 v149, 0xffff0000, v176
	v_lshlrev_b32_e32 v214, 16, v177
	v_and_b32_e32 v215, 0xffff0000, v177
	v_max_f32_e32 v148, 0x800000, v148
	v_max_f32_e32 v149, 0x800000, v149
	v_max_f32_e32 v214, 0x800000, v214
	v_max_f32_e32 v215, 0x800000, v215
	v_rcp_f32_e32 v148, v148
	v_rcp_f32_e32 v149, v149
	v_rcp_f32_e32 v214, v214
	v_rcp_f32_e32 v215, v215
	v_lshlrev_b32_e32 v144, 16, v168
	v_and_b32_e32 v145, 0xffff0000, v168
	v_lshlrev_b32_e32 v146, 16, v169
	v_and_b32_e32 v147, 0xffff0000, v169
	v_mul_f32_e32 v144, v144, v148
	v_mul_f32_e32 v145, v145, v149
	v_mul_f32_e32 v146, v146, v214
	v_mul_f32_e32 v147, v147, v215
	v_pk_mul_f32 v[70:71], v[70:71], v[144:145]
	v_pk_mul_f32 v[72:73], v[72:73], v[146:147]
	v_lshlrev_b32_e32 v148, 16, v178
	v_and_b32_e32 v149, 0xffff0000, v178
	v_lshlrev_b32_e32 v214, 16, v179
	v_and_b32_e32 v215, 0xffff0000, v179
	v_max_f32_e32 v148, 0x800000, v148
	v_max_f32_e32 v149, 0x800000, v149
	v_max_f32_e32 v214, 0x800000, v214
	v_max_f32_e32 v215, 0x800000, v215
	v_rcp_f32_e32 v148, v148
	v_rcp_f32_e32 v149, v149
	v_rcp_f32_e32 v214, v214
	v_rcp_f32_e32 v215, v215
	v_lshlrev_b32_e32 v144, 16, v170
	v_and_b32_e32 v145, 0xffff0000, v170
	v_lshlrev_b32_e32 v146, 16, v171
	v_and_b32_e32 v147, 0xffff0000, v171
	v_mul_f32_e32 v144, v144, v148
	v_mul_f32_e32 v145, v145, v149
	v_mul_f32_e32 v146, v146, v214
	v_mul_f32_e32 v147, v147, v215
	v_pk_mul_f32 v[66:67], v[66:67], v[144:145]
	v_pk_mul_f32 v[68:69], v[68:69], v[146:147]
	v_add_u32_e32 v143, 0x50000, v142
	global_load_dwordx2 v[164:165], v143, s[100:101]
	global_load_dwordx2 v[166:167], v143, s[100:101] offset:32
	global_load_dwordx2 v[168:169], v143, s[100:101] offset:256
	global_load_dwordx2 v[170:171], v143, s[100:101] offset:288
	global_load_dwordx2 v[172:173], v143, s[98:99]
	global_load_dwordx2 v[174:175], v143, s[98:99] offset:32
	global_load_dwordx2 v[176:177], v143, s[98:99] offset:256
	global_load_dwordx2 v[178:179], v143, s[98:99] offset:288
	s_waitcnt vmcnt(16)
; __device__ __forceinline__ unsigned pk2(float lo, float hi) { const f32x2_t_ v = {lo, hi}; return __builtin_bit_cast(unsigned, __builtin_convertvector(v, bf16x2_t_)); }
;     __device__ __forceinline__ Pre pre4(int row, int col) const { const float* sb = (row < TP) ? srcP : srcS - (size_t)TP * DM; Pre p; p.s = NTL((const f32x4*)(sb + (size_t)row * DM + col)); return p; }
;     __device__ __forceinline__ float store4p(int row, int col, f32x4 a, const Pre& p) const {
;         const size_t o = (size_t)row * DM + col;
;         float r0 = bflo(p.g.x) * a[0], r1 = bfhi(p.g.x) * a[1], r2 = bflo(p.g.y) * a[2], r3 = bfhi(p.g.y) * a[3];
;         if (MODE == 1) { r0 += bflo(p.m.x); r1 += bfhi(p.m.x); r2 += bflo(p.m.y); r3 += bfhi(p.m.y); }
;         v2u w; w.x = pk2(r0, r1); w.y = pk2(r2, r3); *(v2u*)(MG + o) = w; return 0.f;
;     }
;     __device__ __forceinline__ float store4(int row, int col, f32x4 a) const {
;         const size_t o = (size_t)row * DM + col; const v2u g = NTL((const v2u*)(SG + o));
;         float r0 = bflo(g.x) * a[0], r1 = bfhi(g.x) * a[1], r2 = bflo(g.y) * a[2], r3 = bfhi(g.y) * a[3];
;         if (MODE == 1) { const v2u p = NTL((const v2u*)(MG + o)); r0 += bflo(p.x); r1 += bfhi(p.x); r2 += bflo(p.y); r3 += bfhi(p.y); }
;         v2u w; w.x = pk2(r0, r1); w.y = pk2(r2, r3); *(v2u*)(MG + o) = w; return 0.f;
;     }
;     __device__ __forceinline__ void operator()(const f32x4 (&acc)[2][2][4][2], const Unit& u, int wr, int wc, int fr, int fq) const {
;         const int row0 = u.pm * BM + wr * 64 + fr, col0 = u.pn * BM + wc * 32 + 4 * fq;
; #pragma unroll
;         for (int am = 0; am < 4; ++am) {
;             const int ai = am >> 1, mb = (am & 1) * 2;
;             Pre pv[2][2][2];
; #pragma unroll
;             for (int mm = 0; mm < 2; ++mm)
; #pragma unroll
;                 for (int bj = 0; bj < 2; ++bj)
; #pragma unroll
;                     for (int n = 0; n < 2; ++n) pv[mm][bj][n] = pre4(row0 + ai * HALF + (mb + mm) * 16, col0 + bj * HALF + n * 16);
; #pragma unroll
;             for (int mm = 0; mm < 2; ++mm)
; #pragma unroll
;                 for (int bj = 0; bj < 2; ++bj)
; #pragma unroll
;                     for (int n = 0; n < 2; ++n) (void)store4p(row0 + ai * HALF + (mb + mm) * 16, col0 + bj * HALF + n * 16, acc[ai][bj][mb + mm][n], pv[mm][bj][n]);
	v_lshlrev_b32_e32 v148, 16, v188
	v_and_b32_e32 v149, 0xffff0000, v188
	v_lshlrev_b32_e32 v214, 16, v189
	v_and_b32_e32 v215, 0xffff0000, v189
	v_max_f32_e32 v148, 0x800000, v148
	v_max_f32_e32 v149, 0x800000, v149
	v_max_f32_e32 v214, 0x800000, v214
	v_max_f32_e32 v215, 0x800000, v215
	v_rcp_f32_e32 v148, v148
	v_rcp_f32_e32 v149, v149
	v_rcp_f32_e32 v214, v214
	v_rcp_f32_e32 v215, v215
	v_lshlrev_b32_e32 v144, 16, v180
	v_and_b32_e32 v145, 0xffff0000, v180
	v_lshlrev_b32_e32 v146, 16, v181
	v_and_b32_e32 v147, 0xffff0000, v181
	v_mul_f32_e32 v144, v144, v148
	v_mul_f32_e32 v145, v145, v149
	v_mul_f32_e32 v146, v146, v214
	v_mul_f32_e32 v147, v147, v215
	v_pk_mul_f32 v[62:63], v[62:63], v[144:145]
	v_pk_mul_f32 v[64:65], v[64:65], v[146:147]
	v_lshlrev_b32_e32 v148, 16, v190
	v_and_b32_e32 v149, 0xffff0000, v190
	v_lshlrev_b32_e32 v214, 16, v191
	v_and_b32_e32 v215, 0xffff0000, v191
	v_max_f32_e32 v148, 0x800000, v148
	v_max_f32_e32 v149, 0x800000, v149
	v_max_f32_e32 v214, 0x800000, v214
	v_max_f32_e32 v215, 0x800000, v215
	v_rcp_f32_e32 v148, v148
	v_rcp_f32_e32 v149, v149
	v_rcp_f32_e32 v214, v214
	v_rcp_f32_e32 v215, v215
	v_lshlrev_b32_e32 v144, 16, v182
	v_and_b32_e32 v145, 0xffff0000, v182
	v_lshlrev_b32_e32 v146, 16, v183
	v_and_b32_e32 v147, 0xffff0000, v183
	v_mul_f32_e32 v144, v144, v148
	v_mul_f32_e32 v145, v145, v149
	v_mul_f32_e32 v146, v146, v214
	v_mul_f32_e32 v147, v147, v215
	v_pk_mul_f32 v[58:59], v[58:59], v[144:145]
	v_pk_mul_f32 v[60:61], v[60:61], v[146:147]
	v_lshlrev_b32_e32 v148, 16, v192
	v_and_b32_e32 v149, 0xffff0000, v192
	v_lshlrev_b32_e32 v214, 16, v193
	v_and_b32_e32 v215, 0xffff0000, v193
	v_max_f32_e32 v148, 0x800000, v148
	v_max_f32_e32 v149, 0x800000, v149
	v_max_f32_e32 v214, 0x800000, v214
	v_max_f32_e32 v215, 0x800000, v215
	v_rcp_f32_e32 v148, v148
	v_rcp_f32_e32 v149, v149
	v_rcp_f32_e32 v214, v214
	v_rcp_f32_e32 v215, v215
	v_lshlrev_b32_e32 v144, 16, v184
	v_and_b32_e32 v145, 0xffff0000, v184
	v_lshlrev_b32_e32 v146, 16, v185
	v_and_b32_e32 v147, 0xffff0000, v185
	v_mul_f32_e32 v144, v144, v148
	v_mul_f32_e32 v145, v145, v149
	v_mul_f32_e32 v146, v146, v214
	v_mul_f32_e32 v147, v147, v215
	v_pk_mul_f32 v[50:51], v[50:51], v[144:145]
	v_pk_mul_f32 v[52:53], v[52:53], v[146:147]
	v_lshlrev_b32_e32 v148, 16, v194
	v_and_b32_e32 v149, 0xffff0000, v194
	v_lshlrev_b32_e32 v214, 16, v195
	v_and_b32_e32 v215, 0xffff0000, v195
	v_max_f32_e32 v148, 0x800000, v148
	v_max_f32_e32 v149, 0x800000, v149
	v_max_f32_e32 v214, 0x800000, v214
	v_max_f32_e32 v215, 0x800000, v215
	v_rcp_f32_e32 v148, v148
	v_rcp_f32_e32 v149, v149
	v_rcp_f32_e32 v214, v214
	v_rcp_f32_e32 v215, v215
	v_lshlrev_b32_e32 v144, 16, v186
	v_and_b32_e32 v145, 0xffff0000, v186
	v_lshlrev_b32_e32 v146, 16, v187
	v_and_b32_e32 v147, 0xffff0000, v187
	v_mul_f32_e32 v144, v144, v148
	v_mul_f32_e32 v145, v145, v149
	v_mul_f32_e32 v146, v146, v214
	v_mul_f32_e32 v147, v147, v215
	v_pk_mul_f32 v[46:47], v[46:47], v[144:145]
	v_pk_mul_f32 v[48:49], v[48:49], v[146:147]
	v_add_u32_e32 v143, 0x58000, v142
	global_load_dwordx2 v[180:181], v143, s[100:101]
	global_load_dwordx2 v[182:183], v143, s[100:101] offset:32
	global_load_dwordx2 v[184:185], v143, s[100:101] offset:256
	global_load_dwordx2 v[186:187], v143, s[100:101] offset:288
	global_load_dwordx2 v[188:189], v143, s[98:99]
	global_load_dwordx2 v[190:191], v143, s[98:99] offset:32
	global_load_dwordx2 v[192:193], v143, s[98:99] offset:256
	global_load_dwordx2 v[194:195], v143, s[98:99] offset:288
	s_waitcnt vmcnt(16)
	v_lshlrev_b32_e32 v148, 16, v204
	v_and_b32_e32 v149, 0xffff0000, v204
	v_lshlrev_b32_e32 v214, 16, v205
	v_and_b32_e32 v215, 0xffff0000, v205
	v_max_f32_e32 v148, 0x800000, v148
	v_max_f32_e32 v149, 0x800000, v149
	v_max_f32_e32 v214, 0x800000, v214
	v_max_f32_e32 v215, 0x800000, v215
	v_rcp_f32_e32 v148, v148
	v_rcp_f32_e32 v149, v149
	v_rcp_f32_e32 v214, v214
	v_rcp_f32_e32 v215, v215
	v_lshlrev_b32_e32 v144, 16, v196
	v_and_b32_e32 v145, 0xffff0000, v196
	v_lshlrev_b32_e32 v146, 16, v197
	v_and_b32_e32 v147, 0xffff0000, v197
	v_mul_f32_e32 v144, v144, v148
	v_mul_f32_e32 v145, v145, v149
	v_mul_f32_e32 v146, v146, v214
	v_mul_f32_e32 v147, v147, v215
	v_pk_mul_f32 v[54:55], v[54:55], v[144:145]
	v_pk_mul_f32 v[56:57], v[56:57], v[146:147]
	v_lshlrev_b32_e32 v148, 16, v206
	v_and_b32_e32 v149, 0xffff0000, v206
	v_lshlrev_b32_e32 v214, 16, v207
	v_and_b32_e32 v215, 0xffff0000, v207
	v_max_f32_e32 v148, 0x800000, v148
	v_max_f32_e32 v149, 0x800000, v149
	v_max_f32_e32 v214, 0x800000, v214
	v_max_f32_e32 v215, 0x800000, v215
	v_rcp_f32_e32 v148, v148
	v_rcp_f32_e32 v149, v149
	v_rcp_f32_e32 v214, v214
	v_rcp_f32_e32 v215, v215
	v_lshlrev_b32_e32 v144, 16, v198
	v_and_b32_e32 v145, 0xffff0000, v198
	v_lshlrev_b32_e32 v146, 16, v199
	v_and_b32_e32 v147, 0xffff0000, v199
	v_mul_f32_e32 v144, v144, v148
	v_mul_f32_e32 v145, v145, v149
	v_mul_f32_e32 v146, v146, v214
	v_mul_f32_e32 v147, v147, v215
	v_pk_mul_f32 v[42:43], v[42:43], v[144:145]
	v_pk_mul_f32 v[44:45], v[44:45], v[146:147]
	v_lshlrev_b32_e32 v148, 16, v208
	v_and_b32_e32 v149, 0xffff0000, v208
	v_lshlrev_b32_e32 v214, 16, v209
	v_and_b32_e32 v215, 0xffff0000, v209
	v_max_f32_e32 v148, 0x800000, v148
	v_max_f32_e32 v149, 0x800000, v149
	v_max_f32_e32 v214, 0x800000, v214
	v_max_f32_e32 v215, 0x800000, v215
	v_rcp_f32_e32 v148, v148
	v_rcp_f32_e32 v149, v149
	v_rcp_f32_e32 v214, v214
	v_rcp_f32_e32 v215, v215
	v_lshlrev_b32_e32 v144, 16, v200
	v_and_b32_e32 v145, 0xffff0000, v200
	v_lshlrev_b32_e32 v146, 16, v201
	v_and_b32_e32 v147, 0xffff0000, v201
	v_mul_f32_e32 v144, v144, v148
	v_mul_f32_e32 v145, v145, v149
	v_mul_f32_e32 v146, v146, v214
	v_mul_f32_e32 v147, v147, v215
	v_pk_mul_f32 v[38:39], v[38:39], v[144:145]
	v_pk_mul_f32 v[40:41], v[40:41], v[146:147]
	v_lshlrev_b32_e32 v148, 16, v210
	v_and_b32_e32 v149, 0xffff0000, v210
	v_lshlrev_b32_e32 v214, 16, v211
	v_and_b32_e32 v215, 0xffff0000, v211
	v_max_f32_e32 v148, 0x800000, v148
	v_max_f32_e32 v149, 0x800000, v149
	v_max_f32_e32 v214, 0x800000, v214
	v_max_f32_e32 v215, 0x800000, v215
	v_rcp_f32_e32 v148, v148
	v_rcp_f32_e32 v149, v149
	v_rcp_f32_e32 v214, v214
	v_rcp_f32_e32 v215, v215
	v_lshlrev_b32_e32 v144, 16, v202
	v_and_b32_e32 v145, 0xffff0000, v202
	v_lshlrev_b32_e32 v146, 16, v203
	v_and_b32_e32 v147, 0xffff0000, v203
	v_mul_f32_e32 v144, v144, v148
	v_mul_f32_e32 v145, v145, v149
	v_mul_f32_e32 v146, v146, v214
	v_mul_f32_e32 v147, v147, v215
	v_pk_mul_f32 v[30:31], v[30:31], v[144:145]
	v_pk_mul_f32 v[32:33], v[32:33], v[146:147]
	s_waitcnt vmcnt(8)
; __device__ __forceinline__ unsigned pk2(float lo, float hi) { const f32x2_t_ v = {lo, hi}; return __builtin_bit_cast(unsigned, __builtin_convertvector(v, bf16x2_t_)); }
;     __device__ __forceinline__ Pre pre4(int row, int col) const { const float* sb = (row < TP) ? srcP : srcS - (size_t)TP * DM; Pre p; p.s = NTL((const f32x4*)(sb + (size_t)row * DM + col)); return p; }
;     __device__ __forceinline__ float store4p(int row, int col, f32x4 a, const Pre& p) const {
;         const size_t o = (size_t)row * DM + col;
;         float r0 = bflo(p.g.x) * a[0], r1 = bfhi(p.g.x) * a[1], r2 = bflo(p.g.y) * a[2], r3 = bfhi(p.g.y) * a[3];
;         if (MODE == 1) { r0 += bflo(p.m.x); r1 += bfhi(p.m.x); r2 += bflo(p.m.y); r3 += bfhi(p.m.y); }
;         v2u w; w.x = pk2(r0, r1); w.y = pk2(r2, r3); *(v2u*)(MG + o) = w; return 0.f;
;     }
;     __device__ __forceinline__ float store4(int row, int col, f32x4 a) const {
;         const size_t o = (size_t)row * DM + col; const v2u g = NTL((const v2u*)(SG + o));
;         float r0 = bflo(g.x) * a[0], r1 = bfhi(g.x) * a[1], r2 = bflo(g.y) * a[2], r3 = bfhi(g.y) * a[3];
;         if (MODE == 1) { const v2u p = NTL((const v2u*)(MG + o)); r0 += bflo(p.x); r1 += bfhi(p.x); r2 += bflo(p.y); r3 += bfhi(p.y); }
;         v2u w; w.x = pk2(r0, r1); w.y = pk2(r2, r3); *(v2u*)(MG + o) = w; return 0.f;
;     }
;     __device__ __forceinline__ void operator()(const f32x4 (&acc)[2][2][4][2], const Unit& u, int wr, int wc, int fr, int fq) const {
;         const int row0 = u.pm * BM + wr * 64 + fr, col0 = u.pn * BM + wc * 32 + 4 * fq;
; #pragma unroll
;         for (int am = 0; am < 4; ++am) {
;             const int ai = am >> 1, mb = (am & 1) * 2;
;             Pre pv[2][2][2];
; #pragma unroll
;             for (int mm = 0; mm < 2; ++mm)
; #pragma unroll
;                 for (int bj = 0; bj < 2; ++bj)
; #pragma unroll
;                     for (int n = 0; n < 2; ++n) pv[mm][bj][n] = pre4(row0 + ai * HALF + (mb + mm) * 16, col0 + bj * HALF + n * 16);
; #pragma unroll
;             for (int mm = 0; mm < 2; ++mm)
; #pragma unroll
;                 for (int bj = 0; bj < 2; ++bj)
; #pragma unroll
;                     for (int n = 0; n < 2; ++n) (void)store4p(row0 + ai * HALF + (mb + mm) * 16, col0 + bj * HALF + n * 16, acc[ai][bj][mb + mm][n], pv[mm][bj][n]);
	v_lshlrev_b32_e32 v148, 16, v172
	v_and_b32_e32 v149, 0xffff0000, v172
	v_lshlrev_b32_e32 v214, 16, v173
	v_and_b32_e32 v215, 0xffff0000, v173
	v_max_f32_e32 v148, 0x800000, v148
	v_max_f32_e32 v149, 0x800000, v149
	v_max_f32_e32 v214, 0x800000, v214
	v_max_f32_e32 v215, 0x800000, v215
	v_rcp_f32_e32 v148, v148
	v_rcp_f32_e32 v149, v149
	v_rcp_f32_e32 v214, v214
	v_rcp_f32_e32 v215, v215
	v_lshlrev_b32_e32 v144, 16, v164
	v_and_b32_e32 v145, 0xffff0000, v164
	v_lshlrev_b32_e32 v146, 16, v165
	v_and_b32_e32 v147, 0xffff0000, v165
	v_mul_f32_e32 v144, v144, v148
	v_mul_f32_e32 v145, v145, v149
	v_mul_f32_e32 v146, v146, v214
	v_mul_f32_e32 v147, v147, v215
	v_pk_mul_f32 v[34:35], v[34:35], v[144:145]
	v_pk_mul_f32 v[36:37], v[36:37], v[146:147]
	v_lshlrev_b32_e32 v148, 16, v174
	v_and_b32_e32 v149, 0xffff0000, v174
	v_lshlrev_b32_e32 v214, 16, v175
	v_and_b32_e32 v215, 0xffff0000, v175
	v_max_f32_e32 v148, 0x800000, v148
	v_max_f32_e32 v149, 0x800000, v149
	v_max_f32_e32 v214, 0x800000, v214
	v_max_f32_e32 v215, 0x800000, v215
	v_rcp_f32_e32 v148, v148
	v_rcp_f32_e32 v149, v149
	v_rcp_f32_e32 v214, v214
	v_rcp_f32_e32 v215, v215
	v_lshlrev_b32_e32 v144, 16, v166
	v_and_b32_e32 v145, 0xffff0000, v166
	v_lshlrev_b32_e32 v146, 16, v167
	v_and_b32_e32 v147, 0xffff0000, v167
	v_mul_f32_e32 v144, v144, v148
	v_mul_f32_e32 v145, v145, v149
	v_mul_f32_e32 v146, v146, v214
	v_mul_f32_e32 v147, v147, v215
	v_pk_mul_f32 v[26:27], v[26:27], v[144:145]
	v_pk_mul_f32 v[28:29], v[28:29], v[146:147]
	v_lshlrev_b32_e32 v148, 16, v176
	v_and_b32_e32 v149, 0xffff0000, v176
	v_lshlrev_b32_e32 v214, 16, v177
	v_and_b32_e32 v215, 0xffff0000, v177
	v_max_f32_e32 v148, 0x800000, v148
	v_max_f32_e32 v149, 0x800000, v149
	v_max_f32_e32 v214, 0x800000, v214
	v_max_f32_e32 v215, 0x800000, v215
	v_rcp_f32_e32 v148, v148
	v_rcp_f32_e32 v149, v149
	v_rcp_f32_e32 v214, v214
	v_rcp_f32_e32 v215, v215
	v_lshlrev_b32_e32 v144, 16, v168
	v_and_b32_e32 v145, 0xffff0000, v168
	v_lshlrev_b32_e32 v146, 16, v169
	v_and_b32_e32 v147, 0xffff0000, v169
	v_mul_f32_e32 v144, v144, v148
	v_mul_f32_e32 v145, v145, v149
	v_mul_f32_e32 v146, v146, v214
	v_mul_f32_e32 v147, v147, v215
	v_pk_mul_f32 v[22:23], v[22:23], v[144:145]
	v_pk_mul_f32 v[24:25], v[24:25], v[146:147]
	v_lshlrev_b32_e32 v148, 16, v178
	v_and_b32_e32 v149, 0xffff0000, v178
	v_lshlrev_b32_e32 v214, 16, v179
	v_and_b32_e32 v215, 0xffff0000, v179
	v_max_f32_e32 v148, 0x800000, v148
	v_max_f32_e32 v149, 0x800000, v149
	v_max_f32_e32 v214, 0x800000, v214
	v_max_f32_e32 v215, 0x800000, v215
	v_rcp_f32_e32 v148, v148
	v_rcp_f32_e32 v149, v149
	v_rcp_f32_e32 v214, v214
	v_rcp_f32_e32 v215, v215
	v_lshlrev_b32_e32 v144, 16, v170
	v_and_b32_e32 v145, 0xffff0000, v170
	v_lshlrev_b32_e32 v146, 16, v171
	v_and_b32_e32 v147, 0xffff0000, v171
	v_mul_f32_e32 v144, v144, v148
	v_mul_f32_e32 v145, v145, v149
	v_mul_f32_e32 v146, v146, v214
	v_mul_f32_e32 v147, v147, v215
	v_pk_mul_f32 v[14:15], v[14:15], v[144:145]
	v_pk_mul_f32 v[16:17], v[16:17], v[146:147]
	s_waitcnt vmcnt(0)
	v_lshlrev_b32_e32 v148, 16, v188
	v_and_b32_e32 v149, 0xffff0000, v188
	v_lshlrev_b32_e32 v214, 16, v189
	v_and_b32_e32 v215, 0xffff0000, v189
	v_max_f32_e32 v148, 0x800000, v148
	v_max_f32_e32 v149, 0x800000, v149
	v_max_f32_e32 v214, 0x800000, v214
	v_max_f32_e32 v215, 0x800000, v215
	v_rcp_f32_e32 v148, v148
	v_rcp_f32_e32 v149, v149
	v_rcp_f32_e32 v214, v214
	v_rcp_f32_e32 v215, v215
	v_lshlrev_b32_e32 v144, 16, v180
	v_and_b32_e32 v145, 0xffff0000, v180
	v_lshlrev_b32_e32 v146, 16, v181
	v_and_b32_e32 v147, 0xffff0000, v181
	v_mul_f32_e32 v144, v144, v148
	v_mul_f32_e32 v145, v145, v149
	v_mul_f32_e32 v146, v146, v214
	v_mul_f32_e32 v147, v147, v215
	v_pk_mul_f32 v[18:19], v[18:19], v[144:145]
	v_pk_mul_f32 v[20:21], v[20:21], v[146:147]
	v_lshlrev_b32_e32 v148, 16, v190
	v_and_b32_e32 v149, 0xffff0000, v190
	v_lshlrev_b32_e32 v214, 16, v191
	v_and_b32_e32 v215, 0xffff0000, v191
	v_max_f32_e32 v148, 0x800000, v148
	v_max_f32_e32 v149, 0x800000, v149
	v_max_f32_e32 v214, 0x800000, v214
	v_max_f32_e32 v215, 0x800000, v215
	v_rcp_f32_e32 v148, v148
	v_rcp_f32_e32 v149, v149
	v_rcp_f32_e32 v214, v214
	v_rcp_f32_e32 v215, v215
	v_lshlrev_b32_e32 v144, 16, v182
	v_and_b32_e32 v145, 0xffff0000, v182
	v_lshlrev_b32_e32 v146, 16, v183
	v_and_b32_e32 v147, 0xffff0000, v183
	v_mul_f32_e32 v144, v144, v148
	v_mul_f32_e32 v145, v145, v149
	v_mul_f32_e32 v146, v146, v214
	v_mul_f32_e32 v147, v147, v215
	v_pk_mul_f32 v[10:11], v[10:11], v[144:145]
	v_pk_mul_f32 v[12:13], v[12:13], v[146:147]
	v_lshlrev_b32_e32 v148, 16, v192
	v_and_b32_e32 v149, 0xffff0000, v192
	v_lshlrev_b32_e32 v214, 16, v193
	v_and_b32_e32 v215, 0xffff0000, v193
	v_max_f32_e32 v148, 0x800000, v148
	v_max_f32_e32 v149, 0x800000, v149
	v_max_f32_e32 v214, 0x800000, v214
	v_max_f32_e32 v215, 0x800000, v215
	v_rcp_f32_e32 v148, v148
	v_rcp_f32_e32 v149, v149
	v_rcp_f32_e32 v214, v214
	v_rcp_f32_e32 v215, v215
	v_lshlrev_b32_e32 v144, 16, v184
	v_and_b32_e32 v145, 0xffff0000, v184
	v_lshlrev_b32_e32 v146, 16, v185
	v_and_b32_e32 v147, 0xffff0000, v185
	v_mul_f32_e32 v144, v144, v148
	v_mul_f32_e32 v145, v145, v149
	v_mul_f32_e32 v146, v146, v214
	v_mul_f32_e32 v147, v147, v215
	v_pk_mul_f32 v[6:7], v[6:7], v[144:145]
	v_pk_mul_f32 v[8:9], v[8:9], v[146:147]
	v_lshlrev_b32_e32 v148, 16, v194
	v_and_b32_e32 v149, 0xffff0000, v194
	v_lshlrev_b32_e32 v214, 16, v195
	v_and_b32_e32 v215, 0xffff0000, v195
	v_max_f32_e32 v148, 0x800000, v148
	v_max_f32_e32 v149, 0x800000, v149
	v_max_f32_e32 v214, 0x800000, v214
	v_max_f32_e32 v215, 0x800000, v215
	v_rcp_f32_e32 v148, v148
	v_rcp_f32_e32 v149, v149
	v_rcp_f32_e32 v214, v214
	v_rcp_f32_e32 v215, v215
	v_lshlrev_b32_e32 v144, 16, v186
	v_and_b32_e32 v145, 0xffff0000, v186
	v_lshlrev_b32_e32 v146, 16, v187
	v_and_b32_e32 v147, 0xffff0000, v187
	v_mul_f32_e32 v144, v144, v148
	v_mul_f32_e32 v145, v145, v149
	v_mul_f32_e32 v146, v146, v214
	v_mul_f32_e32 v147, v147, v215
	v_pk_mul_f32 v[2:3], v[2:3], v[144:145]
	v_pk_mul_f32 v[4:5], v[4:5], v[146:147]
	v_mov_b32_e32 v212, v2
	v_mov_b32_e32 v213, v3
	v_mov_b32_e32 v214, v4
	v_mov_b32_e32 v215, v5
	v_mov_b32_e32 v216, v6
	v_mov_b32_e32 v217, v7
	v_mov_b32_e32 v218, v8
	v_mov_b32_e32 v219, v9
	s_andn2_b64 vcc, exec, s[6:7]
	s_mov_b64 s[6:7], -1
	s_cbranch_vccnz .LBB0_1569
	s_andn2_b64 vcc, exec, s[16:17]
	s_cbranch_vccnz .LBB0_1568
	s_barrier
	s_branch .LBB0_1568

; template <class Epi, class Sched, bool ALIGN_EPI = false, bool SP2 = false>
; __device__ __forceinline__ void gemm_phase(PG8_LAS unsigned char* lds, const Gemm g, const Sched& S, const Epi& E) {
;     ...
;     f32x4 acc[2][2][4][2];
; #pragma unroll
;     for (int a = 0; a < 2; ++a)
; #pragma unroll
;         for (int b = 0; b < 2; ++b)
; #pragma unroll
;             for (int m = 0; m < 4; ++m)
; #pragma unroll
;                 for (int n = 0; n < 2; ++n) acc[a][b][m][n] = (f32x4){0.f, 0.f, 0.f, 0.f};
;     bf16x8 At[4][2], B0[2][2], B1[2][2];
;     const char* cA = (const char*)g.A + (size_t)cur.pm * tstep; const char* cB = (const char*)g.Bt + (size_t)cur.pn * tstep;
;     ...
;         const bool has_next = S.next(ui + 1, nxt);
;         const char* nA = has_next ? (const char*)g.A + (size_t)nxt.pm * tstep : cA; const char* nB = has_next ? (const char*)g.Bt + (size_t)nxt.pn * tstep : cB;
.LBB0_1600:
	s_ashr_i32 s49, s48, 31
	s_lshl_b64 s[34:35], s[48:49], 18
	s_add_u32 s50, s36, s34
	s_addc_u32 s51, s37, s35
	s_and_b64 s[34:35], s[6:7], exec
	s_cselect_b32 s49, s51, s57
	s_cselect_b32 s72, s50, s56
	s_ashr_i32 s47, s46, 31
	s_lshl_b64 s[34:35], s[46:47], 18
	s_add_u32 s52, s38, s34
	s_addc_u32 s53, s39, s35
	s_and_b64 s[34:35], s[6:7], exec
	s_cselect_b32 s47, s53, s59
	s_cselect_b32 s73, s52, s58
	s_add_u32 s56, s56, 0x20080
	s_addc_u32 s57, s57, 0
	s_add_u32 s76, s58, 0x100
	v_mov_b32_e32 v2, 0
	s_addc_u32 s77, s59, 0
	s_mov_b32 s78, -2
	v_mov_b32_e32 v2, v212
	v_mov_b32_e32 v3, v213
	v_mov_b32_e32 v4, v214
	v_mov_b32_e32 v5, v215
	v_mov_b32_e32 v6, v216
	v_mov_b32_e32 v7, v217
	v_mov_b32_e32 v8, v218
	v_mov_b32_e32 v9, v219
	s_waitcnt vmcnt(0)
	v_mov_b32_e32 v160, v118
	v_mov_b32_e32 v161, v119
	v_mov_b32_e32 v162, v120
	v_mov_b32_e32 v163, v121
	v_mov_b32_e32 v118, v114
	v_mov_b32_e32 v119, v115
	v_mov_b32_e32 v120, v116
	v_mov_b32_e32 v121, v117
	v_mov_b32_e32 v114, v160
	v_mov_b32_e32 v115, v161
	v_mov_b32_e32 v116, v162
	v_mov_b32_e32 v117, v163
	v_mov_b32_e32 v160, v98
	v_mov_b32_e32 v161, v99
	v_mov_b32_e32 v162, v100
	v_mov_b32_e32 v163, v101
	v_mov_b32_e32 v98, v94
	v_mov_b32_e32 v99, v95
	v_mov_b32_e32 v100, v96
	v_mov_b32_e32 v101, v97
	v_mov_b32_e32 v94, v160
	v_mov_b32_e32 v95, v161
	v_mov_b32_e32 v96, v162
	v_mov_b32_e32 v97, v163
	v_mov_b32_e32 v160, v86
	v_mov_b32_e32 v161, v87
	v_mov_b32_e32 v162, v88
	v_mov_b32_e32 v163, v89
	v_mov_b32_e32 v86, v82
	v_mov_b32_e32 v87, v83
	v_mov_b32_e32 v88, v84
	v_mov_b32_e32 v89, v85
	v_mov_b32_e32 v82, v160
	v_mov_b32_e32 v83, v161
	v_mov_b32_e32 v84, v162
	v_mov_b32_e32 v85, v163
	v_mov_b32_e32 v160, v54
	v_mov_b32_e32 v161, v55
	v_mov_b32_e32 v162, v56
	v_mov_b32_e32 v163, v57
	v_mov_b32_e32 v54, v50
	v_mov_b32_e32 v55, v51
	v_mov_b32_e32 v56, v52
	v_mov_b32_e32 v57, v53
	v_mov_b32_e32 v50, v160
	v_mov_b32_e32 v51, v161
	v_mov_b32_e32 v52, v162
	v_mov_b32_e32 v53, v163
	v_mov_b32_e32 v160, v34
	v_mov_b32_e32 v161, v35
	v_mov_b32_e32 v162, v36
	v_mov_b32_e32 v163, v37
	v_mov_b32_e32 v34, v30
	v_mov_b32_e32 v35, v31
	v_mov_b32_e32 v36, v32
	v_mov_b32_e32 v37, v33
	v_mov_b32_e32 v30, v160
	v_mov_b32_e32 v31, v161
	v_mov_b32_e32 v32, v162
	v_mov_b32_e32 v33, v163

; __device__ __forceinline__ unsigned pk2(float lo, float hi) { const f32x2_t_ v = {lo, hi}; return __builtin_bit_cast(unsigned, __builtin_convertvector(v, bf16x2_t_)); }
;     __device__ __forceinline__ Pre pre4(int row, int col) const { const float* sb = (row < TP) ? srcP : srcS - (size_t)TP * DM; Pre p; p.s = NTL((const f32x4*)(sb + (size_t)row * DM + col)); return p; }
;     __device__ __forceinline__ float store4p(int row, int col, f32x4 a, const Pre& p) const {
;         const size_t o = (size_t)row * DM + col;
;         float r0 = bflo(p.g.x) * a[0], r1 = bfhi(p.g.x) * a[1], r2 = bflo(p.g.y) * a[2], r3 = bfhi(p.g.y) * a[3];
;         if (MODE == 1) { r0 += bflo(p.m.x); r1 += bfhi(p.m.x); r2 += bflo(p.m.y); r3 += bfhi(p.m.y); }
;         v2u w; w.x = pk2(r0, r1); w.y = pk2(r2, r3); *(v2u*)(MG + o) = w; return 0.f;
;     }
;     __device__ __forceinline__ float store4(int row, int col, f32x4 a) const {
;         const size_t o = (size_t)row * DM + col; const v2u g = NTL((const v2u*)(SG + o));
;         float r0 = bflo(g.x) * a[0], r1 = bfhi(g.x) * a[1], r2 = bflo(g.y) * a[2], r3 = bfhi(g.y) * a[3];
;         if (MODE == 1) { const v2u p = NTL((const v2u*)(MG + o)); r0 += bflo(p.x); r1 += bfhi(p.x); r2 += bflo(p.y); r3 += bfhi(p.y); }
;         v2u w; w.x = pk2(r0, r1); w.y = pk2(r2, r3); *(v2u*)(MG + o) = w; return 0.f;
;     }
;     __device__ __forceinline__ void operator()(const f32x4 (&acc)[2][2][4][2], const Unit& u, int wr, int wc, int fr, int fq) const {
;         const int row0 = u.pm * BM + wr * 64 + fr, col0 = u.pn * BM + wc * 32 + 4 * fq;
; #pragma unroll
;         for (int am = 0; am < 4; ++am) {
;             const int ai = am >> 1, mb = (am & 1) * 2;
;             Pre pv[2][2][2];
; #pragma unroll
;             for (int mm = 0; mm < 2; ++mm)
; #pragma unroll
;                 for (int bj = 0; bj < 2; ++bj)
; #pragma unroll
;                     for (int n = 0; n < 2; ++n) pv[mm][bj][n] = pre4(row0 + ai * HALF + (mb + mm) * 16, col0 + bj * HALF + n * 16);
; #pragma unroll
;             for (int mm = 0; mm < 2; ++mm)
; #pragma unroll
;                 for (int bj = 0; bj < 2; ++bj)
; #pragma unroll
;                     for (int n = 0; n < 2; ++n) (void)store4p(row0 + ai * HALF + (mb + mm) * 16, col0 + bj * HALF + n * 16, acc[ai][bj][mb + mm][n], pv[mm][bj][n]);
.LBB0_1604:
	s_lshl_b32 s100, s54, 19
	s_lshl_b32 s101, s71, 9
	s_add_i32 s100, s100, s101
	s_add_u32 s98, s16, s100
	s_addc_u32 s99, s17, 0
	s_add_u32 s100, s10, s100
	s_addc_u32 s101, s11, 0
	v_lshlrev_b32_e32 v142, 11, v157
	v_lshl_add_u32 v142, v155, 1, v142
	v_mov_b32_e32 v144, v142
	global_load_dwordx2 v[160:161], v144, s[98:99]
	global_load_dwordx2 v[162:163], v144, s[98:99] offset:32
	global_load_dwordx2 v[164:165], v144, s[98:99] offset:256
	global_load_dwordx2 v[166:167], v144, s[98:99] offset:288
	v_add_u32_e32 v145, 0x8000, v142
	global_load_dwordx2 v[168:169], v145, s[98:99]
	global_load_dwordx2 v[170:171], v145, s[98:99] offset:32
	global_load_dwordx2 v[172:173], v145, s[98:99] offset:256
	global_load_dwordx2 v[174:175], v145, s[98:99] offset:288
	v_add_u32_e32 v146, 0x10000, v142
	global_load_dwordx2 v[176:177], v146, s[98:99]
	global_load_dwordx2 v[178:179], v146, s[98:99] offset:32
	global_load_dwordx2 v[180:181], v146, s[98:99] offset:256
	global_load_dwordx2 v[182:183], v146, s[98:99] offset:288
	s_waitcnt vmcnt(8)
	v_lshlrev_b32_e32 v148, 16, v160
	v_and_b32_e32 v149, 0xffff0000, v160
	v_lshlrev_b32_e32 v150, 16, v161
	v_and_b32_e32 v151, 0xffff0000, v161
	v_pk_mul_f32 v[126:127], v[126:127], v[148:149]
	v_pk_mul_f32 v[128:129], v[128:129], v[150:151]
	v_cvt_pk_bf16_f32 v126, v126, v127
	v_cvt_pk_bf16_f32 v127, v128, v129
	global_store_dwordx2 v144, v[126:127], s[100:101]
	v_lshlrev_b32_e32 v148, 16, v162
	v_and_b32_e32 v149, 0xffff0000, v162
	v_lshlrev_b32_e32 v150, 16, v163
	v_and_b32_e32 v151, 0xffff0000, v163
	v_pk_mul_f32 v[122:123], v[122:123], v[148:149]
	v_pk_mul_f32 v[124:125], v[124:125], v[150:151]
	v_cvt_pk_bf16_f32 v122, v122, v123
	v_cvt_pk_bf16_f32 v123, v124, v125
	global_store_dwordx2 v144, v[122:123], s[100:101] offset:32
	v_lshlrev_b32_e32 v148, 16, v164
	v_and_b32_e32 v149, 0xffff0000, v164
	v_lshlrev_b32_e32 v150, 16, v165
	v_and_b32_e32 v151, 0xffff0000, v165
	v_pk_mul_f32 v[118:119], v[118:119], v[148:149]
	v_pk_mul_f32 v[120:121], v[120:121], v[150:151]
	v_cvt_pk_bf16_f32 v118, v118, v119
	v_cvt_pk_bf16_f32 v119, v120, v121
	global_store_dwordx2 v144, v[118:119], s[100:101] offset:256
	v_lshlrev_b32_e32 v148, 16, v166
	v_and_b32_e32 v149, 0xffff0000, v166
	v_lshlrev_b32_e32 v150, 16, v167
	v_and_b32_e32 v151, 0xffff0000, v167
	v_pk_mul_f32 v[110:111], v[110:111], v[148:149]
	v_pk_mul_f32 v[112:113], v[112:113], v[150:151]
	v_cvt_pk_bf16_f32 v110, v110, v111
	v_cvt_pk_bf16_f32 v111, v112, v113
	global_store_dwordx2 v144, v[110:111], s[100:101] offset:288
	v_add_u32_e32 v144, 0x18000, v142
	global_load_dwordx2 v[160:161], v144, s[98:99]
	global_load_dwordx2 v[162:163], v144, s[98:99] offset:32
	global_load_dwordx2 v[164:165], v144, s[98:99] offset:256
	global_load_dwordx2 v[166:167], v144, s[98:99] offset:288
	s_waitcnt vmcnt(12)
	v_lshlrev_b32_e32 v148, 16, v168
	v_and_b32_e32 v149, 0xffff0000, v168
	v_lshlrev_b32_e32 v150, 16, v169
	v_and_b32_e32 v151, 0xffff0000, v169
	v_pk_mul_f32 v[114:115], v[114:115], v[148:149]
	v_pk_mul_f32 v[116:117], v[116:117], v[150:151]
	v_cvt_pk_bf16_f32 v114, v114, v115
	v_cvt_pk_bf16_f32 v115, v116, v117
	global_store_dwordx2 v145, v[114:115], s[100:101]
	v_lshlrev_b32_e32 v148, 16, v170
	v_and_b32_e32 v149, 0xffff0000, v170
	v_lshlrev_b32_e32 v150, 16, v171
	v_and_b32_e32 v151, 0xffff0000, v171
	v_pk_mul_f32 v[106:107], v[106:107], v[148:149]
	v_pk_mul_f32 v[108:109], v[108:109], v[150:151]
	v_cvt_pk_bf16_f32 v106, v106, v107
	v_cvt_pk_bf16_f32 v107, v108, v109
	global_store_dwordx2 v145, v[106:107], s[100:101] offset:32
	v_lshlrev_b32_e32 v148, 16, v172
	v_and_b32_e32 v149, 0xffff0000, v172
	v_lshlrev_b32_e32 v150, 16, v173
	v_and_b32_e32 v151, 0xffff0000, v173
	v_pk_mul_f32 v[102:103], v[102:103], v[148:149]
	v_pk_mul_f32 v[104:105], v[104:105], v[150:151]
	v_cvt_pk_bf16_f32 v102, v102, v103
	v_cvt_pk_bf16_f32 v103, v104, v105
	global_store_dwordx2 v145, v[102:103], s[100:101] offset:256
	v_lshlrev_b32_e32 v148, 16, v174
	v_and_b32_e32 v149, 0xffff0000, v174
	v_lshlrev_b32_e32 v150, 16, v175
	v_and_b32_e32 v151, 0xffff0000, v175
	v_pk_mul_f32 v[98:99], v[98:99], v[148:149]
	v_pk_mul_f32 v[100:101], v[100:101], v[150:151]
	v_cvt_pk_bf16_f32 v98, v98, v99
	v_cvt_pk_bf16_f32 v99, v100, v101
	global_store_dwordx2 v145, v[98:99], s[100:101] offset:288
	v_add_u32_e32 v145, 0x40000, v142
	global_load_dwordx2 v[168:169], v145, s[98:99]
	global_load_dwordx2 v[170:171], v145, s[98:99] offset:32
	global_load_dwordx2 v[172:173], v145, s[98:99] offset:256
	global_load_dwordx2 v[174:175], v145, s[98:99] offset:288
	s_waitcnt vmcnt(16)
	v_lshlrev_b32_e32 v148, 16, v176
	v_and_b32_e32 v149, 0xffff0000, v176
	v_lshlrev_b32_e32 v150, 16, v177
	v_and_b32_e32 v151, 0xffff0000, v177
	v_pk_mul_f32 v[94:95], v[94:95], v[148:149]
	v_pk_mul_f32 v[96:97], v[96:97], v[150:151]
	v_cvt_pk_bf16_f32 v94, v94, v95
	v_cvt_pk_bf16_f32 v95, v96, v97
	global_store_dwordx2 v146, v[94:95], s[100:101]
	v_lshlrev_b32_e32 v148, 16, v178
	v_and_b32_e32 v149, 0xffff0000, v178
	v_lshlrev_b32_e32 v150, 16, v179
	v_and_b32_e32 v151, 0xffff0000, v179
	v_pk_mul_f32 v[90:91], v[90:91], v[148:149]
	v_pk_mul_f32 v[92:93], v[92:93], v[150:151]
	v_cvt_pk_bf16_f32 v90, v90, v91
	v_cvt_pk_bf16_f32 v91, v92, v93
	global_store_dwordx2 v146, v[90:91], s[100:101] offset:32
	v_lshlrev_b32_e32 v148, 16, v180
	v_and_b32_e32 v149, 0xffff0000, v180
	v_lshlrev_b32_e32 v150, 16, v181
	v_and_b32_e32 v151, 0xffff0000, v181
	v_pk_mul_f32 v[86:87], v[86:87], v[148:149]
	v_pk_mul_f32 v[88:89], v[88:89], v[150:151]
	v_cvt_pk_bf16_f32 v86, v86, v87
	v_cvt_pk_bf16_f32 v87, v88, v89
	global_store_dwordx2 v146, v[86:87], s[100:101] offset:256
	v_lshlrev_b32_e32 v148, 16, v182
	v_and_b32_e32 v149, 0xffff0000, v182
	v_lshlrev_b32_e32 v150, 16, v183
	v_and_b32_e32 v151, 0xffff0000, v183
	v_pk_mul_f32 v[78:79], v[78:79], v[148:149]
	v_pk_mul_f32 v[80:81], v[80:81], v[150:151]
	v_cvt_pk_bf16_f32 v78, v78, v79
	v_cvt_pk_bf16_f32 v79, v80, v81
	global_store_dwordx2 v146, v[78:79], s[100:101] offset:288
	v_add_u32_e32 v146, 0x48000, v142
	global_load_dwordx2 v[176:177], v146, s[98:99]
	global_load_dwordx2 v[178:179], v146, s[98:99] offset:32
	global_load_dwordx2 v[180:181], v146, s[98:99] offset:256
	global_load_dwordx2 v[182:183], v146, s[98:99] offset:288
	s_waitcnt vmcnt(16)
; __device__ __forceinline__ unsigned pk2(float lo, float hi) { const f32x2_t_ v = {lo, hi}; return __builtin_bit_cast(unsigned, __builtin_convertvector(v, bf16x2_t_)); }
;     __device__ __forceinline__ Pre pre4(int row, int col) const { const float* sb = (row < TP) ? srcP : srcS - (size_t)TP * DM; Pre p; p.s = NTL((const f32x4*)(sb + (size_t)row * DM + col)); return p; }
;     __device__ __forceinline__ float store4p(int row, int col, f32x4 a, const Pre& p) const {
;         const size_t o = (size_t)row * DM + col;
;         float r0 = bflo(p.g.x) * a[0], r1 = bfhi(p.g.x) * a[1], r2 = bflo(p.g.y) * a[2], r3 = bfhi(p.g.y) * a[3];
;         if (MODE == 1) { r0 += bflo(p.m.x); r1 += bfhi(p.m.x); r2 += bflo(p.m.y); r3 += bfhi(p.m.y); }
;         v2u w; w.x = pk2(r0, r1); w.y = pk2(r2, r3); *(v2u*)(MG + o) = w; return 0.f;
;     }
;     __device__ __forceinline__ float store4(int row, int col, f32x4 a) const {
;         const size_t o = (size_t)row * DM + col; const v2u g = NTL((const v2u*)(SG + o));
;         float r0 = bflo(g.x) * a[0], r1 = bfhi(g.x) * a[1], r2 = bflo(g.y) * a[2], r3 = bfhi(g.y) * a[3];
;         if (MODE == 1) { const v2u p = NTL((const v2u*)(MG + o)); r0 += bflo(p.x); r1 += bfhi(p.x); r2 += bflo(p.y); r3 += bfhi(p.y); }
;         v2u w; w.x = pk2(r0, r1); w.y = pk2(r2, r3); *(v2u*)(MG + o) = w; return 0.f;
;     }
;     __device__ __forceinline__ void operator()(const f32x4 (&acc)[2][2][4][2], const Unit& u, int wr, int wc, int fr, int fq) const {
;         const int row0 = u.pm * BM + wr * 64 + fr, col0 = u.pn * BM + wc * 32 + 4 * fq;
; #pragma unroll
;         for (int am = 0; am < 4; ++am) {
;             const int ai = am >> 1, mb = (am & 1) * 2;
;             Pre pv[2][2][2];
; #pragma unroll
;             for (int mm = 0; mm < 2; ++mm)
; #pragma unroll
;                 for (int bj = 0; bj < 2; ++bj)
; #pragma unroll
;                     for (int n = 0; n < 2; ++n) pv[mm][bj][n] = pre4(row0 + ai * HALF + (mb + mm) * 16, col0 + bj * HALF + n * 16);
; #pragma unroll
;             for (int mm = 0; mm < 2; ++mm)
; #pragma unroll
;                 for (int bj = 0; bj < 2; ++bj)
; #pragma unroll
;                     for (int n = 0; n < 2; ++n) (void)store4p(row0 + ai * HALF + (mb + mm) * 16, col0 + bj * HALF + n * 16, acc[ai][bj][mb + mm][n], pv[mm][bj][n]);
	v_lshlrev_b32_e32 v148, 16, v160
	v_and_b32_e32 v149, 0xffff0000, v160
	v_lshlrev_b32_e32 v150, 16, v161
	v_and_b32_e32 v151, 0xffff0000, v161
	v_pk_mul_f32 v[82:83], v[82:83], v[148:149]
	v_pk_mul_f32 v[84:85], v[84:85], v[150:151]
	v_cvt_pk_bf16_f32 v82, v82, v83
	v_cvt_pk_bf16_f32 v83, v84, v85
	global_store_dwordx2 v144, v[82:83], s[100:101]
	v_lshlrev_b32_e32 v148, 16, v162
	v_and_b32_e32 v149, 0xffff0000, v162
	v_lshlrev_b32_e32 v150, 16, v163
	v_and_b32_e32 v151, 0xffff0000, v163
	v_pk_mul_f32 v[74:75], v[74:75], v[148:149]
	v_pk_mul_f32 v[76:77], v[76:77], v[150:151]
	v_cvt_pk_bf16_f32 v74, v74, v75
	v_cvt_pk_bf16_f32 v75, v76, v77
	global_store_dwordx2 v144, v[74:75], s[100:101] offset:32
	v_lshlrev_b32_e32 v148, 16, v164
	v_and_b32_e32 v149, 0xffff0000, v164
	v_lshlrev_b32_e32 v150, 16, v165
	v_and_b32_e32 v151, 0xffff0000, v165
	v_pk_mul_f32 v[70:71], v[70:71], v[148:149]
	v_pk_mul_f32 v[72:73], v[72:73], v[150:151]
	v_cvt_pk_bf16_f32 v70, v70, v71
	v_cvt_pk_bf16_f32 v71, v72, v73
	global_store_dwordx2 v144, v[70:71], s[100:101] offset:256
	v_lshlrev_b32_e32 v148, 16, v166
	v_and_b32_e32 v149, 0xffff0000, v166
	v_lshlrev_b32_e32 v150, 16, v167
	v_and_b32_e32 v151, 0xffff0000, v167
	v_pk_mul_f32 v[66:67], v[66:67], v[148:149]
	v_pk_mul_f32 v[68:69], v[68:69], v[150:151]
	v_cvt_pk_bf16_f32 v66, v66, v67
	v_cvt_pk_bf16_f32 v67, v68, v69
	global_store_dwordx2 v144, v[66:67], s[100:101] offset:288
	v_add_u32_e32 v144, 0x50000, v142
	global_load_dwordx2 v[160:161], v144, s[98:99]
	global_load_dwordx2 v[162:163], v144, s[98:99] offset:32
	global_load_dwordx2 v[164:165], v144, s[98:99] offset:256
	global_load_dwordx2 v[166:167], v144, s[98:99] offset:288
	s_waitcnt vmcnt(16)
	v_lshlrev_b32_e32 v148, 16, v168
	v_and_b32_e32 v149, 0xffff0000, v168
	v_lshlrev_b32_e32 v150, 16, v169
	v_and_b32_e32 v151, 0xffff0000, v169
	v_pk_mul_f32 v[62:63], v[62:63], v[148:149]
	v_pk_mul_f32 v[64:65], v[64:65], v[150:151]
	v_cvt_pk_bf16_f32 v62, v62, v63
	v_cvt_pk_bf16_f32 v63, v64, v65
	global_store_dwordx2 v145, v[62:63], s[100:101]
	v_lshlrev_b32_e32 v148, 16, v170
	v_and_b32_e32 v149, 0xffff0000, v170
	v_lshlrev_b32_e32 v150, 16, v171
	v_and_b32_e32 v151, 0xffff0000, v171
	v_pk_mul_f32 v[58:59], v[58:59], v[148:149]
	v_pk_mul_f32 v[60:61], v[60:61], v[150:151]
	v_cvt_pk_bf16_f32 v58, v58, v59
	v_cvt_pk_bf16_f32 v59, v60, v61
	global_store_dwordx2 v145, v[58:59], s[100:101] offset:32
	v_lshlrev_b32_e32 v148, 16, v172
	v_and_b32_e32 v149, 0xffff0000, v172
	v_lshlrev_b32_e32 v150, 16, v173
	v_and_b32_e32 v151, 0xffff0000, v173
	v_pk_mul_f32 v[54:55], v[54:55], v[148:149]
	v_pk_mul_f32 v[56:57], v[56:57], v[150:151]
	v_cvt_pk_bf16_f32 v54, v54, v55
	v_cvt_pk_bf16_f32 v55, v56, v57
	global_store_dwordx2 v145, v[54:55], s[100:101] offset:256
	v_lshlrev_b32_e32 v148, 16, v174
	v_and_b32_e32 v149, 0xffff0000, v174
	v_lshlrev_b32_e32 v150, 16, v175
	v_and_b32_e32 v151, 0xffff0000, v175
	v_pk_mul_f32 v[46:47], v[46:47], v[148:149]
	v_pk_mul_f32 v[48:49], v[48:49], v[150:151]
	v_cvt_pk_bf16_f32 v46, v46, v47
	v_cvt_pk_bf16_f32 v47, v48, v49
	global_store_dwordx2 v145, v[46:47], s[100:101] offset:288
	v_add_u32_e32 v145, 0x58000, v142
	global_load_dwordx2 v[168:169], v145, s[98:99]
	global_load_dwordx2 v[170:171], v145, s[98:99] offset:32
	global_load_dwordx2 v[172:173], v145, s[98:99] offset:256
	global_load_dwordx2 v[174:175], v145, s[98:99] offset:288
	s_waitcnt vmcnt(16)
; __device__ __forceinline__ unsigned pk2(float lo, float hi) { const f32x2_t_ v = {lo, hi}; return __builtin_bit_cast(unsigned, __builtin_convertvector(v, bf16x2_t_)); }
;     __device__ __forceinline__ Pre pre4(int row, int col) const { const float* sb = (row < TP) ? srcP : srcS - (size_t)TP * DM; Pre p; p.s = NTL((const f32x4*)(sb + (size_t)row * DM + col)); return p; }
;     __device__ __forceinline__ float store4p(int row, int col, f32x4 a, const Pre& p) const {
;         const size_t o = (size_t)row * DM + col;
;         float r0 = bflo(p.g.x) * a[0], r1 = bfhi(p.g.x) * a[1], r2 = bflo(p.g.y) * a[2], r3 = bfhi(p.g.y) * a[3];
;         if (MODE == 1) { r0 += bflo(p.m.x); r1 += bfhi(p.m.x); r2 += bflo(p.m.y); r3 += bfhi(p.m.y); }
;         v2u w; w.x = pk2(r0, r1); w.y = pk2(r2, r3); *(v2u*)(MG + o) = w; return 0.f;
;     }
;     __device__ __forceinline__ float store4(int row, int col, f32x4 a) const {
;         const size_t o = (size_t)row * DM + col; const v2u g = NTL((const v2u*)(SG + o));
;         float r0 = bflo(g.x) * a[0], r1 = bfhi(g.x) * a[1], r2 = bflo(g.y) * a[2], r3 = bfhi(g.y) * a[3];
;         if (MODE == 1) { const v2u p = NTL((const v2u*)(MG + o)); r0 += bflo(p.x); r1 += bfhi(p.x); r2 += bflo(p.y); r3 += bfhi(p.y); }
;         v2u w; w.x = pk2(r0, r1); w.y = pk2(r2, r3); *(v2u*)(MG + o) = w; return 0.f;
;     }
;     __device__ __forceinline__ void operator()(const f32x4 (&acc)[2][2][4][2], const Unit& u, int wr, int wc, int fr, int fq) const {
;         const int row0 = u.pm * BM + wr * 64 + fr, col0 = u.pn * BM + wc * 32 + 4 * fq;
; #pragma unroll
;         for (int am = 0; am < 4; ++am) {
;             const int ai = am >> 1, mb = (am & 1) * 2;
;             Pre pv[2][2][2];
; #pragma unroll
;             for (int mm = 0; mm < 2; ++mm)
; #pragma unroll
;                 for (int bj = 0; bj < 2; ++bj)
; #pragma unroll
;                     for (int n = 0; n < 2; ++n) pv[mm][bj][n] = pre4(row0 + ai * HALF + (mb + mm) * 16, col0 + bj * HALF + n * 16);
; #pragma unroll
;             for (int mm = 0; mm < 2; ++mm)
; #pragma unroll
;                 for (int bj = 0; bj < 2; ++bj)
; #pragma unroll
;                     for (int n = 0; n < 2; ++n) (void)store4p(row0 + ai * HALF + (mb + mm) * 16, col0 + bj * HALF + n * 16, acc[ai][bj][mb + mm][n], pv[mm][bj][n]);
	v_lshlrev_b32_e32 v148, 16, v176
	v_and_b32_e32 v149, 0xffff0000, v176
	v_lshlrev_b32_e32 v150, 16, v177
	v_and_b32_e32 v151, 0xffff0000, v177
	v_pk_mul_f32 v[50:51], v[50:51], v[148:149]
	v_pk_mul_f32 v[52:53], v[52:53], v[150:151]
	v_cvt_pk_bf16_f32 v50, v50, v51
	v_cvt_pk_bf16_f32 v51, v52, v53
	global_store_dwordx2 v146, v[50:51], s[100:101]
	v_lshlrev_b32_e32 v148, 16, v178
	v_and_b32_e32 v149, 0xffff0000, v178
	v_lshlrev_b32_e32 v150, 16, v179
	v_and_b32_e32 v151, 0xffff0000, v179
	v_pk_mul_f32 v[42:43], v[42:43], v[148:149]
	v_pk_mul_f32 v[44:45], v[44:45], v[150:151]
	v_cvt_pk_bf16_f32 v42, v42, v43
	v_cvt_pk_bf16_f32 v43, v44, v45
	global_store_dwordx2 v146, v[42:43], s[100:101] offset:32
	v_lshlrev_b32_e32 v148, 16, v180
	v_and_b32_e32 v149, 0xffff0000, v180
	v_lshlrev_b32_e32 v150, 16, v181
	v_and_b32_e32 v151, 0xffff0000, v181
	v_pk_mul_f32 v[38:39], v[38:39], v[148:149]
	v_pk_mul_f32 v[40:41], v[40:41], v[150:151]
	v_cvt_pk_bf16_f32 v38, v38, v39
	v_cvt_pk_bf16_f32 v39, v40, v41
	global_store_dwordx2 v146, v[38:39], s[100:101] offset:256
	v_lshlrev_b32_e32 v148, 16, v182
	v_and_b32_e32 v149, 0xffff0000, v182
	v_lshlrev_b32_e32 v150, 16, v183
	v_and_b32_e32 v151, 0xffff0000, v183
	v_pk_mul_f32 v[34:35], v[34:35], v[148:149]
	v_pk_mul_f32 v[36:37], v[36:37], v[150:151]
	v_cvt_pk_bf16_f32 v34, v34, v35
	v_cvt_pk_bf16_f32 v35, v36, v37
	global_store_dwordx2 v146, v[34:35], s[100:101] offset:288
	s_waitcnt vmcnt(12)
	v_lshlrev_b32_e32 v148, 16, v160
	v_and_b32_e32 v149, 0xffff0000, v160
	v_lshlrev_b32_e32 v150, 16, v161
	v_and_b32_e32 v151, 0xffff0000, v161
	v_pk_mul_f32 v[30:31], v[30:31], v[148:149]
	v_pk_mul_f32 v[32:33], v[32:33], v[150:151]
	v_cvt_pk_bf16_f32 v30, v30, v31
	v_cvt_pk_bf16_f32 v31, v32, v33
	global_store_dwordx2 v144, v[30:31], s[100:101]
	v_lshlrev_b32_e32 v148, 16, v162
	v_and_b32_e32 v149, 0xffff0000, v162
	v_lshlrev_b32_e32 v150, 16, v163
	v_and_b32_e32 v151, 0xffff0000, v163
	v_pk_mul_f32 v[26:27], v[26:27], v[148:149]
	v_pk_mul_f32 v[28:29], v[28:29], v[150:151]
	v_cvt_pk_bf16_f32 v26, v26, v27
	v_cvt_pk_bf16_f32 v27, v28, v29
	global_store_dwordx2 v144, v[26:27], s[100:101] offset:32
	v_lshlrev_b32_e32 v148, 16, v164
	v_and_b32_e32 v149, 0xffff0000, v164
	v_lshlrev_b32_e32 v150, 16, v165
	v_and_b32_e32 v151, 0xffff0000, v165
	v_pk_mul_f32 v[22:23], v[22:23], v[148:149]
	v_pk_mul_f32 v[24:25], v[24:25], v[150:151]
	v_cvt_pk_bf16_f32 v22, v22, v23
	v_cvt_pk_bf16_f32 v23, v24, v25
	global_store_dwordx2 v144, v[22:23], s[100:101] offset:256
	v_lshlrev_b32_e32 v148, 16, v166
	v_and_b32_e32 v149, 0xffff0000, v166
	v_lshlrev_b32_e32 v150, 16, v167
	v_and_b32_e32 v151, 0xffff0000, v167
	v_pk_mul_f32 v[14:15], v[14:15], v[148:149]
	v_pk_mul_f32 v[16:17], v[16:17], v[150:151]
	v_cvt_pk_bf16_f32 v14, v14, v15
	v_cvt_pk_bf16_f32 v15, v16, v17
	global_store_dwordx2 v144, v[14:15], s[100:101] offset:288
	s_waitcnt vmcnt(8)
	v_lshlrev_b32_e32 v148, 16, v168
	v_and_b32_e32 v149, 0xffff0000, v168
	v_lshlrev_b32_e32 v150, 16, v169
	v_and_b32_e32 v151, 0xffff0000, v169
	v_pk_mul_f32 v[18:19], v[18:19], v[148:149]
	v_pk_mul_f32 v[20:21], v[20:21], v[150:151]
	v_cvt_pk_bf16_f32 v18, v18, v19
	v_cvt_pk_bf16_f32 v19, v20, v21
	global_store_dwordx2 v145, v[18:19], s[100:101]
	v_lshlrev_b32_e32 v148, 16, v170
	v_and_b32_e32 v149, 0xffff0000, v170
	v_lshlrev_b32_e32 v150, 16, v171
	v_and_b32_e32 v151, 0xffff0000, v171
	v_pk_mul_f32 v[10:11], v[10:11], v[148:149]
	v_pk_mul_f32 v[12:13], v[12:13], v[150:151]
	v_cvt_pk_bf16_f32 v10, v10, v11
	v_cvt_pk_bf16_f32 v11, v12, v13
	global_store_dwordx2 v145, v[10:11], s[100:101] offset:32
	v_lshlrev_b32_e32 v148, 16, v172
	v_and_b32_e32 v149, 0xffff0000, v172
	v_lshlrev_b32_e32 v150, 16, v173
	v_and_b32_e32 v151, 0xffff0000, v173
	v_pk_mul_f32 v[6:7], v[6:7], v[148:149]
	v_pk_mul_f32 v[8:9], v[8:9], v[150:151]
	v_cvt_pk_bf16_f32 v6, v6, v7
	v_cvt_pk_bf16_f32 v7, v8, v9
	global_store_dwordx2 v145, v[6:7], s[100:101] offset:256
	v_lshlrev_b32_e32 v148, 16, v174
	v_and_b32_e32 v149, 0xffff0000, v174
	v_lshlrev_b32_e32 v150, 16, v175
	v_and_b32_e32 v151, 0xffff0000, v175
	v_pk_mul_f32 v[2:3], v[2:3], v[148:149]
	v_pk_mul_f32 v[4:5], v[4:5], v[150:151]
	v_cvt_pk_bf16_f32 v2, v2, v3
	v_cvt_pk_bf16_f32 v3, v4, v5
	global_store_dwordx2 v145, v[2:3], s[100:101] offset:288
	s_andn2_b64 vcc, exec, s[6:7]
	s_mov_b64 s[6:7], -1
	s_cbranch_vccnz .LBB0_1593
	s_andn2_b64 vcc, exec, s[40:41]
	s_cbranch_vccnz .LBB0_1592
	s_barrier
	s_branch .LBB0_1592
